# v32 + neighbourhood-attention QK: same-accumulator MFMA pairs back to back, refill ds_reads grouped after each pair, counted waits re-derived
# baseline (speedup 1.0000x reference)
.LBB0_2818:
	s_cmp_gt_u32 s49, 3
	s_cselect_b64 s[12:13], -1, 0
	s_cmp_lt_u32 s49, 4
	s_cselect_b64 s[8:9], -1, 0
	s_add_i32 s49, s15, s47
	s_cmp_ge_i32 s49, s28
	s_cselect_b64 s[50:51], -1, 0
	s_cmp_lt_i32 s49, s43
	s_cselect_b64 s[52:53], -1, 0
	s_and_b64 s[50:51], s[50:51], s[52:53]
	s_or_b64 s[8:9], s[8:9], s[50:51]
	s_andn2_b64 vcc, exec, s[8:9]
	s_cbranch_vccnz .LBB0_2891
	v_add_u32_e32 v0, s44, v202
	ds_read_b128 v[2:5], v0
	ds_read_b128 v[112:115], v0 offset:8192
	v_add_u32_e32 v0, s44, v203
	ds_read_b128 v[116:119], v0
	ds_read_b128 v[120:123], v0 offset:8192
	v_add_u32_e32 v0, s44, v204
	ds_read_b128 v[124:127], v0
	ds_read_b128 v[128:131], v0 offset:8192
	v_add_u32_e32 v0, s44, v205
	ds_read_b128 v[132:135], v0
	ds_read_b128 v[136:139], v0 offset:8192
	v_xor_b32_e32 v80, 0x80000000, v210
	v_mov_b32_e32 v81, v80
	v_mov_b32_e32 v82, v80
	v_mov_b32_e32 v83, v80
	v_mov_b32_e32 v84, v80
	v_mov_b32_e32 v85, v80
	v_mov_b32_e32 v86, v80
	v_mov_b32_e32 v87, v80
	v_mov_b32_e32 v88, v80
	v_mov_b32_e32 v89, v80
	v_mov_b32_e32 v90, v80
	v_mov_b32_e32 v91, v80
	v_mov_b32_e32 v92, v80
	v_mov_b32_e32 v93, v80
	v_mov_b32_e32 v94, v80
	v_mov_b32_e32 v95, v80
	s_andn2_b64 vcc, exec, s[12:13]
	s_waitcnt lgkmcnt(5)
	v_mfma_f32_32x32x16_bf16 v[96:111], v[2:5], v[144:147], v[80:95]
	v_mfma_f32_32x32x16_bf16 v[96:111], v[116:119], v[148:151], v[96:111]
	v_add_u32_e32 v0, s44, v206
	ds_read_b128 v[2:5], v0
	v_add_u32_e32 v0, s44, v207
	ds_read_b128 v[116:119], v0
	s_waitcnt lgkmcnt(6)
	v_mfma_f32_32x32x16_bf16 v[80:95], v[112:115], v[144:147], v[80:95]
	v_mfma_f32_32x32x16_bf16 v[80:95], v[120:123], v[148:151], v[80:95]
	v_add_u32_e32 v0, s44, v206
	ds_read_b128 v[112:115], v0 offset:8192
	v_add_u32_e32 v0, s44, v207
	ds_read_b128 v[120:123], v0 offset:8192
	s_waitcnt lgkmcnt(5)
	v_mfma_f32_32x32x16_bf16 v[96:111], v[124:127], v[152:155], v[96:111]
	v_mfma_f32_32x32x16_bf16 v[96:111], v[132:135], v[156:159], v[96:111]
	v_add_u32_e32 v0, s44, v208
	ds_read_b128 v[124:127], v0
	v_add_u32_e32 v0, s44, v209
	ds_read_b128 v[132:135], v0
	s_waitcnt lgkmcnt(6)
	v_mfma_f32_32x32x16_bf16 v[80:95], v[128:131], v[152:155], v[80:95]
	v_mfma_f32_32x32x16_bf16 v[80:95], v[136:139], v[156:159], v[80:95]
	v_add_u32_e32 v0, s44, v208
	ds_read_b128 v[128:131], v0 offset:8192
	v_add_u32_e32 v0, s44, v209
	ds_read_b128 v[136:139], v0 offset:8192
	s_waitcnt lgkmcnt(6)
	v_mfma_f32_32x32x16_bf16 v[96:111], v[2:5], v[160:163], v[96:111]
	v_mfma_f32_32x32x16_bf16 v[96:111], v[116:119], v[164:167], v[96:111]
	s_waitcnt lgkmcnt(4)
	v_mfma_f32_32x32x16_bf16 v[80:95], v[112:115], v[160:163], v[80:95]
	v_mfma_f32_32x32x16_bf16 v[80:95], v[120:123], v[164:167], v[80:95]
	s_waitcnt lgkmcnt(2)
	v_mfma_f32_32x32x16_bf16 v[96:111], v[124:127], v[168:171], v[96:111]
	v_mfma_f32_32x32x16_bf16 v[96:111], v[132:135], v[172:175], v[96:111]
	s_waitcnt lgkmcnt(0)
	v_mfma_f32_32x32x16_bf16 v[80:95], v[128:131], v[168:171], v[80:95]
	v_mfma_f32_32x32x16_bf16 v[80:95], v[136:139], v[172:175], v[80:95]
	s_nop 1
	s_cbranch_vccnz .LBB0_2885
	v_lshlrev_b32_e32 v0, 2, v197
	v_mov_b32_e32 v5, 0xf149f2ca
	v_add_u32_e32 v0, s46, v0
	ds_read_b32 v128, v0
	ds_read_b32 v129, v0 offset:4
	ds_read_b32 v130, v0 offset:8
	ds_read_b32 v131, v0 offset:12
	ds_read_b32 v132, v0 offset:16
	ds_read_b32 v133, v0 offset:20
	ds_read_b32 v134, v0 offset:24
	ds_read_b32 v135, v0 offset:28
	ds_read_b32 v136, v0 offset:64
	ds_read_b32 v137, v0 offset:68
	ds_read_b32 v138, v0 offset:72
	ds_read_b32 v139, v0 offset:76
	ds_read_b32 v140, v0 offset:80
	ds_read_b32 v141, v0 offset:84
	ds_read_b32 v142, v0 offset:88
	ds_read_b32 v143, v0 offset:92
	ds_read_b32 v112, v0 offset:128
	ds_read_b32 v113, v0 offset:132
	ds_read_b32 v114, v0 offset:136
	ds_read_b32 v115, v0 offset:140
	ds_read_b32 v116, v0 offset:144
	ds_read_b32 v117, v0 offset:148
	ds_read_b32 v118, v0 offset:152
	ds_read_b32 v119, v0 offset:156
	ds_read_b32 v120, v0 offset:192
	ds_read_b32 v121, v0 offset:196
	ds_read_b32 v122, v0 offset:200
	ds_read_b32 v123, v0 offset:204
	ds_read_b32 v124, v0 offset:208
	ds_read_b32 v125, v0 offset:212
	ds_read_b32 v126, v0 offset:216
	ds_read_b32 v127, v0 offset:220
	s_waitcnt lgkmcnt(15)
	v_add_u32_e32 v3, 15, v196
	v_cmp_gt_u32_e32 vcc, 16, v3
	v_add_f32_e32 v96, v96, v128
	v_add_u32_e32 v4, 14, v196
	v_cndmask_b32_e32 v96, v5, v96, vcc
	v_cmp_gt_u32_e32 vcc, 16, v4
	v_add_f32_e32 v97, v97, v129
	v_add_u32_e32 v3, 13, v196
	v_cndmask_b32_e32 v97, v5, v97, vcc
	v_cmp_gt_u32_e32 vcc, 16, v3
	v_add_f32_e32 v98, v98, v130
	v_add_u32_e32 v4, 12, v196
	v_cndmask_b32_e32 v98, v5, v98, vcc
	v_cmp_gt_u32_e32 vcc, 16, v4
	v_add_f32_e32 v99, v99, v131
	v_add_u32_e32 v3, 11, v196
	v_cndmask_b32_e32 v99, v5, v99, vcc
	v_cmp_gt_u32_e32 vcc, 16, v3
	v_add_f32_e32 v100, v100, v132
	v_add_u32_e32 v4, 10, v196
	v_cndmask_b32_e32 v100, v5, v100, vcc
	v_cmp_gt_u32_e32 vcc, 16, v4
	v_add_f32_e32 v101, v101, v133
	v_add_u32_e32 v3, 9, v196
	v_cndmask_b32_e32 v101, v5, v101, vcc
	v_cmp_gt_u32_e32 vcc, 16, v3
	v_add_f32_e32 v102, v102, v134
	v_add_u32_e32 v4, 8, v196
	v_cndmask_b32_e32 v102, v5, v102, vcc
	v_cmp_gt_u32_e32 vcc, 16, v4
	v_add_f32_e32 v103, v103, v135
	v_add_u32_e32 v3, -1, v196
	v_cndmask_b32_e32 v103, v5, v103, vcc
	v_cmp_gt_u32_e32 vcc, 16, v3
	v_add_f32_e32 v104, v104, v136
	v_add_u32_e32 v4, -2, v196
	v_cndmask_b32_e32 v104, v5, v104, vcc
	v_cmp_gt_u32_e32 vcc, 16, v4
	v_add_f32_e32 v105, v105, v137
	v_add_u32_e32 v3, -3, v196
	v_cndmask_b32_e32 v105, v5, v105, vcc
	v_cmp_gt_u32_e32 vcc, 16, v3
	v_add_f32_e32 v106, v106, v138
	v_add_u32_e32 v4, -4, v196
	v_cndmask_b32_e32 v106, v5, v106, vcc
	v_cmp_gt_u32_e32 vcc, 16, v4
	v_add_f32_e32 v107, v107, v139
	v_add_u32_e32 v3, -5, v196
	v_cndmask_b32_e32 v107, v5, v107, vcc
	v_cmp_gt_u32_e32 vcc, 16, v3
	v_add_f32_e32 v108, v108, v140
	v_add_u32_e32 v4, -6, v196
	v_cndmask_b32_e32 v108, v5, v108, vcc
	v_cmp_gt_u32_e32 vcc, 16, v4
	v_add_f32_e32 v109, v109, v141
	v_add_u32_e32 v3, -7, v196
	v_cndmask_b32_e32 v109, v5, v109, vcc
	v_cmp_gt_u32_e32 vcc, 16, v3
	v_add_f32_e32 v110, v110, v142
	v_add_u32_e32 v4, -8, v196
	v_cndmask_b32_e32 v110, v5, v110, vcc
	v_cmp_gt_u32_e32 vcc, 16, v4
	v_add_f32_e32 v111, v111, v143
	v_add_u32_e32 v3, 0xffffffef, v196
	v_cndmask_b32_e32 v111, v5, v111, vcc
	s_waitcnt lgkmcnt(0)
	v_cmp_gt_u32_e32 vcc, 16, v3
	v_add_f32_e32 v80, v80, v112
	v_add_u32_e32 v4, 0xffffffee, v196
	v_cndmask_b32_e32 v80, v5, v80, vcc
	v_cmp_gt_u32_e32 vcc, 16, v4
	v_add_f32_e32 v81, v81, v113
	v_add_u32_e32 v3, 0xffffffed, v196
	v_cndmask_b32_e32 v81, v5, v81, vcc
	v_cmp_gt_u32_e32 vcc, 16, v3
	v_add_f32_e32 v82, v82, v114
	v_add_u32_e32 v4, 0xffffffec, v196
	v_cndmask_b32_e32 v82, v5, v82, vcc
	v_cmp_gt_u32_e32 vcc, 16, v4
	v_add_f32_e32 v83, v83, v115
	v_add_u32_e32 v3, 0xffffffeb, v196
	v_cndmask_b32_e32 v83, v5, v83, vcc
	v_cmp_gt_u32_e32 vcc, 16, v3
	v_add_f32_e32 v84, v84, v116
	v_add_u32_e32 v4, 0xffffffea, v196
	v_cndmask_b32_e32 v84, v5, v84, vcc
	v_cmp_gt_u32_e32 vcc, 16, v4
	v_add_f32_e32 v85, v85, v117
	v_add_u32_e32 v3, 0xffffffe9, v196
	v_cndmask_b32_e32 v85, v5, v85, vcc
	v_cmp_gt_u32_e32 vcc, 16, v3
	v_add_f32_e32 v86, v86, v118
	v_add_u32_e32 v4, 0xffffffe8, v196
	v_cndmask_b32_e32 v86, v5, v86, vcc
	v_cmp_gt_u32_e32 vcc, 16, v4
	v_add_f32_e32 v87, v87, v119
	v_add_u32_e32 v3, 0xffffffdf, v196
	v_cndmask_b32_e32 v87, v5, v87, vcc
	v_cmp_gt_u32_e32 vcc, 16, v3
	v_add_f32_e32 v88, v88, v120
	v_add_u32_e32 v4, 0xffffffde, v196
	v_cndmask_b32_e32 v88, v5, v88, vcc
	v_cmp_gt_u32_e32 vcc, 16, v4
	v_add_f32_e32 v89, v89, v121
	v_add_u32_e32 v3, 0xffffffdd, v196
	v_cndmask_b32_e32 v89, v5, v89, vcc
	v_cmp_gt_u32_e32 vcc, 16, v3
	v_add_f32_e32 v90, v90, v122
	v_add_u32_e32 v4, 0xffffffdc, v196
	v_cndmask_b32_e32 v90, v5, v90, vcc
	v_cmp_gt_u32_e32 vcc, 16, v4
	v_add_f32_e32 v91, v91, v123
	v_add_u32_e32 v3, 0xffffffdb, v196
	v_cndmask_b32_e32 v91, v5, v91, vcc
	v_cmp_gt_u32_e32 vcc, 16, v3
	v_add_f32_e32 v92, v92, v124
	v_add_u32_e32 v4, 0xffffffda, v196
	v_cndmask_b32_e32 v92, v5, v92, vcc
	v_cmp_gt_u32_e32 vcc, 16, v4
	v_add_f32_e32 v93, v93, v125
	v_add_u32_e32 v3, 0xffffffd9, v196
	v_cndmask_b32_e32 v93, v5, v93, vcc
	v_cmp_gt_u32_e32 vcc, 16, v3
	v_add_f32_e32 v94, v94, v126
	v_add_u32_e32 v4, 0xffffffd8, v196
	v_cndmask_b32_e32 v94, v5, v94, vcc
	v_cmp_gt_u32_e32 vcc, 16, v4
	v_add_f32_e32 v95, v95, v127
	s_nop 0
	v_cndmask_b32_e32 v95, v5, v95, vcc
